# pool phase of layer 1: pool_cols<16> row loads issued back to back (16 in flight) instead of one at a time; on top of v38
# speedup vs baseline: 1.0255x; 1.0044x over previous
.LBB0_374:
	v_readlane_b32 s0, v252, 21
	v_readlane_b32 s1, v252, 22
	s_andn2_b64 vcc, exec, s[18:19]
	s_nop 0
	v_cndmask_b32_e64 v0, 0, 1, s[0:1]
	v_cmp_ne_u32_e64 s[2:3], 1, v0
	s_cbranch_vccnz .LBB0_377
	s_and_b64 vcc, exec, s[2:3]
	s_cbranch_vccnz .LBB0_380
	v_readlane_b32 s0, v251, 33
	v_readlane_b32 s1, v251, 34
	s_nop 1
	v_lshl_add_u64 v[2:3], v[30:31], 0, s[0:1]
	flat_load_dword v184, v[2:3]
	v_readlane_b32 s0, v251, 13
	v_readlane_b32 s1, v251, 14
	s_nop 1
	v_lshl_add_u64 v[2:3], v[30:31], 0, s[0:1]
	flat_load_dword v185, v[2:3]
	v_readlane_b32 s0, v251, 15
	v_readlane_b32 s1, v251, 16
	s_nop 1
	v_lshl_add_u64 v[2:3], v[30:31], 0, s[0:1]
	flat_load_dword v186, v[2:3]
	v_readlane_b32 s0, v251, 17
	v_readlane_b32 s1, v251, 18
	s_nop 1
	v_lshl_add_u64 v[2:3], v[30:31], 0, s[0:1]
	flat_load_dword v187, v[2:3]
	v_readlane_b32 s0, v251, 19
	v_readlane_b32 s1, v251, 20
	s_nop 1
	v_lshl_add_u64 v[2:3], v[30:31], 0, s[0:1]
	flat_load_dword v188, v[2:3]
	v_readlane_b32 s0, v251, 25
	v_readlane_b32 s1, v251, 26
	s_nop 1
	v_lshl_add_u64 v[2:3], v[30:31], 0, s[0:1]
	flat_load_dword v189, v[2:3]
	v_readlane_b32 s0, v251, 27
	v_readlane_b32 s1, v251, 28
	s_nop 1
	v_lshl_add_u64 v[2:3], v[30:31], 0, s[0:1]
	flat_load_dword v190, v[2:3]
	v_readlane_b32 s0, v251, 29
	v_readlane_b32 s1, v251, 30
	s_nop 1
	v_lshl_add_u64 v[2:3], v[30:31], 0, s[0:1]
	flat_load_dword v191, v[2:3]
	v_readlane_b32 s0, v253, 39
	v_readlane_b32 s1, v253, 40
	s_nop 1
	v_lshl_add_u64 v[2:3], v[30:31], 0, s[0:1]
	flat_load_dword v192, v[2:3]
	v_readlane_b32 s0, v251, 5
	v_readlane_b32 s1, v251, 6
	s_nop 1
	v_lshl_add_u64 v[2:3], v[30:31], 0, s[0:1]
	flat_load_dword v193, v[2:3]
	v_readlane_b32 s0, v250, 22
	v_readlane_b32 s1, v250, 23
	s_nop 1
	v_lshl_add_u64 v[2:3], v[30:31], 0, s[0:1]
	flat_load_dword v194, v[2:3]
	v_readlane_b32 s0, v251, 31
	v_readlane_b32 s1, v251, 32
	s_nop 1
	v_lshl_add_u64 v[2:3], v[30:31], 0, s[0:1]
	flat_load_dword v195, v[2:3]
	v_readlane_b32 s0, v251, 39
	v_readlane_b32 s1, v251, 40
	s_nop 1
	v_lshl_add_u64 v[2:3], v[30:31], 0, s[0:1]
	flat_load_dword v196, v[2:3]
	v_readlane_b32 s0, v251, 35
	v_readlane_b32 s1, v251, 36
	s_nop 1
	v_lshl_add_u64 v[2:3], v[30:31], 0, s[0:1]
	flat_load_dword v197, v[2:3]
	v_readlane_b32 s0, v252, 5
	v_readlane_b32 s1, v252, 6
	s_nop 1
	v_lshl_add_u64 v[2:3], v[30:31], 0, s[0:1]
	flat_load_dword v198, v[2:3]
	v_readlane_b32 s0, v253, 47
	v_readlane_b32 s1, v253, 48
	s_nop 1
	v_lshl_add_u64 v[2:3], v[30:31], 0, s[0:1]
	flat_load_dword v0, v[2:3]
	s_waitcnt vmcnt(0) lgkmcnt(0)
	v_lshlrev_b32_e32 v48, 16, v184
	v_and_b32_e32 v49, 0xffff0000, v184
	v_lshlrev_b32_e32 v50, 16, v185
	v_and_b32_e32 v51, 0xffff0000, v185
	v_lshlrev_b32_e32 v52, 16, v186
	v_and_b32_e32 v53, 0xffff0000, v186
	v_lshlrev_b32_e32 v54, 16, v187
	v_and_b32_e32 v55, 0xffff0000, v187
	v_lshlrev_b32_e32 v80, 16, v188
	v_and_b32_e32 v81, 0xffff0000, v188
	v_lshlrev_b32_e32 v82, 16, v189
	v_and_b32_e32 v83, 0xffff0000, v189
	v_lshlrev_b32_e32 v34, 16, v190
	v_and_b32_e32 v35, 0xffff0000, v190
	v_lshlrev_b32_e32 v36, 16, v191
	v_and_b32_e32 v37, 0xffff0000, v191
	v_lshlrev_b32_e32 v38, 16, v192
	v_and_b32_e32 v39, 0xffff0000, v192
	v_lshlrev_b32_e32 v40, 16, v193
	v_and_b32_e32 v41, 0xffff0000, v193
	v_lshlrev_b32_e32 v42, 16, v194
	v_and_b32_e32 v43, 0xffff0000, v194
	v_lshlrev_b32_e32 v62, 16, v195
	v_and_b32_e32 v63, 0xffff0000, v195
	v_lshlrev_b32_e32 v64, 16, v196
	v_and_b32_e32 v65, 0xffff0000, v196
	v_lshlrev_b32_e32 v66, 16, v197
	v_and_b32_e32 v67, 0xffff0000, v197
	v_lshlrev_b32_e32 v68, 16, v198
	v_and_b32_e32 v69, 0xffff0000, v198
	ds_read_b128 v[44:47], v1
	ds_read_b128 v[72:75], v1 offset:16
	ds_read_b128 v[76:79], v1 offset:32
	ds_read_b128 v[2:5], v1 offset:48
	s_waitcnt lgkmcnt(0)
	v_pk_mul_f32 v[56:57], v[28:29], v[44:45] op_sel_hi:[1,0]
	v_pk_mul_f32 v[44:45], v[28:29], v[44:45] op_sel:[0,1]
	v_pk_mul_f32 v[124:125], v[56:57], v[48:49]
	v_pk_mul_f32 v[60:61], v[44:45], v[50:51]
	v_pk_mul_f32 v[44:45], v[28:29], v[46:47] op_sel_hi:[1,0]
	s_waitcnt vmcnt(0)
	v_lshlrev_b32_e32 v70, 16, v0
	v_and_b32_e32 v71, 0xffff0000, v0
	v_mov_b32_e32 v0, v47
	v_pk_mul_f32 v[58:59], v[44:45], v[52:53]
	v_pk_mul_f32 v[44:45], v[28:29], v[0:1] op_sel_hi:[1,0]
	v_mov_b32_e32 v0, v75
	v_pk_mul_f32 v[56:57], v[44:45], v[54:55]
	v_pk_mul_f32 v[44:45], v[28:29], v[72:73] op_sel_hi:[1,0]
	s_nop 0
	v_pk_mul_f32 v[54:55], v[44:45], v[80:81]
	v_pk_mul_f32 v[44:45], v[28:29], v[72:73] op_sel:[0,1]
	s_nop 0
	v_pk_mul_f32 v[50:51], v[44:45], v[82:83]
	v_pk_mul_f32 v[44:45], v[28:29], v[74:75] op_sel_hi:[1,0]
	s_nop 0
	v_pk_mul_f32 v[52:53], v[44:45], v[34:35]
	v_pk_mul_f32 v[34:35], v[28:29], v[0:1] op_sel_hi:[1,0]
	v_mov_b32_e32 v0, v79
	v_pk_mul_f32 v[48:49], v[34:35], v[36:37]
	v_pk_mul_f32 v[34:35], v[28:29], v[76:77] op_sel_hi:[1,0]
	s_nop 0
	v_pk_mul_f32 v[46:47], v[34:35], v[38:39]
	v_pk_mul_f32 v[34:35], v[28:29], v[76:77] op_sel:[0,1]
	s_nop 0
	v_pk_mul_f32 v[44:45], v[34:35], v[40:41]
	v_pk_mul_f32 v[34:35], v[28:29], v[78:79] op_sel_hi:[1,0]
	s_nop 0
	v_pk_mul_f32 v[42:43], v[34:35], v[42:43]
	v_pk_mul_f32 v[34:35], v[28:29], v[0:1] op_sel_hi:[1,0]
	v_mov_b32_e32 v0, v5
	v_pk_mul_f32 v[40:41], v[34:35], v[62:63]
	v_pk_mul_f32 v[34:35], v[28:29], v[2:3] op_sel_hi:[1,0]
	v_pk_mul_f32 v[2:3], v[28:29], v[2:3] op_sel:[0,1]
	v_pk_mul_f32 v[38:39], v[34:35], v[64:65]
	v_pk_mul_f32 v[36:37], v[2:3], v[66:67]
	v_pk_mul_f32 v[2:3], v[28:29], v[4:5] op_sel_hi:[1,0]
	s_nop 0
	v_pk_mul_f32 v[34:35], v[2:3], v[68:69]
	v_pk_mul_f32 v[2:3], v[28:29], v[0:1] op_sel_hi:[1,0]
	s_nop 0
	v_pk_mul_f32 v[4:5], v[2:3], v[70:71]
	s_branch .LBB0_381

.LBB0_382:
	v_lshl_add_u64 v[94:95], v[2:3], 0, s[16:17]
	s_mov_b32 s0, 0x30900000
	v_add_co_u32_e32 v32, vcc, s0, v94
	s_mov_b32 s0, 0x30901000
	s_nop 0
	v_addc_co_u32_e32 v33, vcc, 0, v95, vcc
	flat_load_dword v184, v[32:33]
	v_add_co_u32_e32 v32, vcc, s0, v94
	s_mov_b32 s0, 0x30902000
	s_nop 0
	v_addc_co_u32_e32 v33, vcc, 0, v95, vcc
	s_mov_b32 s1, 0x3090d000
	s_add_i32 s28, s19, 1
	s_min_u32 s28, s28, 15
	s_add_i32 s28, s28, 1
	s_add_i32 s29, s19, 2
	s_add_i32 s76, s19, 3
	s_add_i32 s77, s19, 4
	s_add_i32 s26, s19, 5
	s_min_u32 s26, s26, 15
	s_add_i32 s26, s26, 1
	s_add_i32 s27, s19, 6
	s_add_i32 s82, s19, 7
	s_add_i32 s87, s19, 8
	s_add_i32 s72, s19, 9
	s_add_i32 s81, s19, 10
	s_add_i32 s70, s19, 11
	s_add_i32 s71, s19, 12
	s_nop 1
	flat_load_dword v185, v[32:33]
	v_add_co_u32_e32 v32, vcc, s0, v94
	s_mov_b32 s0, 0x30903000
	s_nop 0
	v_addc_co_u32_e32 v33, vcc, 0, v95, vcc
	s_nop 1
	flat_load_dword v186, v[32:33]
	v_add_co_u32_e32 v32, vcc, s0, v94
	s_mov_b32 s0, 0x30904000
	s_nop 0
	v_addc_co_u32_e32 v33, vcc, 0, v95, vcc
	s_nop 1
	flat_load_dword v187, v[32:33]
	v_add_co_u32_e32 v32, vcc, s0, v94
	s_mov_b32 s0, 0x30905000
	s_nop 0
	v_addc_co_u32_e32 v33, vcc, 0, v95, vcc
	s_nop 1
	flat_load_dword v188, v[32:33]
	v_add_co_u32_e32 v32, vcc, s0, v94
	s_mov_b32 s0, 0x30906000
	s_nop 0
	v_addc_co_u32_e32 v33, vcc, 0, v95, vcc
	s_nop 1
	flat_load_dword v189, v[32:33]
	v_add_co_u32_e32 v32, vcc, s0, v94
	s_mov_b32 s0, 0x30907000
	s_nop 0
	v_addc_co_u32_e32 v33, vcc, 0, v95, vcc
	s_nop 1
	flat_load_dword v190, v[32:33]
	v_add_co_u32_e32 v32, vcc, s0, v94
	s_mov_b32 s0, 0x30908000
	s_nop 0
	v_addc_co_u32_e32 v33, vcc, 0, v95, vcc
	s_nop 1
	flat_load_dword v191, v[32:33]
	v_add_co_u32_e32 v32, vcc, s0, v94
	s_mov_b32 s0, 0x30909000
	s_nop 0
	v_addc_co_u32_e32 v33, vcc, 0, v95, vcc
	s_nop 1
	flat_load_dword v192, v[32:33]
	v_add_co_u32_e32 v32, vcc, s0, v94
	s_mov_b32 s0, 0x3090a000
	s_nop 0
	v_addc_co_u32_e32 v33, vcc, 0, v95, vcc
	s_nop 1
	flat_load_dword v193, v[32:33]
	v_add_co_u32_e32 v32, vcc, s0, v94
	s_mov_b32 s0, 0x3090b000
	s_nop 0
	v_addc_co_u32_e32 v33, vcc, 0, v95, vcc
	s_nop 1
	flat_load_dword v194, v[32:33]
	v_add_co_u32_e32 v32, vcc, s0, v94
	s_mov_b32 s0, 0x3090c000
	s_nop 0
	v_addc_co_u32_e32 v33, vcc, 0, v95, vcc
	s_nop 1
	flat_load_dword v195, v[32:33]
	v_add_co_u32_e32 v32, vcc, s0, v94
	s_add_i32 s0, s19, 13
	s_nop 0
	v_addc_co_u32_e32 v33, vcc, 0, v95, vcc
	s_min_u32 s0, s0, 15
	s_add_i32 s0, s0, 1
	s_nop 1
	flat_load_dword v196, v[32:33]
	v_add_co_u32_e32 v32, vcc, s1, v94
	s_add_i32 s1, s19, 14
	s_nop 0
	v_addc_co_u32_e32 v33, vcc, 0, v95, vcc
	s_mov_b32 vcc_lo, 0x3090e000
	s_nop 1
	flat_load_dword v197, v[32:33]
	v_add_co_u32_e32 v32, vcc, vcc_lo, v94
	s_nop 1
	v_addc_co_u32_e32 v33, vcc, 0, v95, vcc
	flat_load_dword v198, v[32:33]
	s_mov_b32 vcc_lo, 0x3090f000
	v_add_co_u32_e32 v32, vcc, vcc_lo, v94
	s_nop 1
	v_addc_co_u32_e32 v33, vcc, 0, v95, vcc
	flat_load_dword v199, v[32:33]
	s_min_u32 vcc_lo, s19, 15
	s_add_i32 vcc_lo, vcc_lo, 1
	s_nop 1
	s_waitcnt vmcnt(0) lgkmcnt(0)
	v_lshlrev_b32_e32 v154, 16, v184
	v_and_b32_e32 v155, 0xffff0000, v184
	v_lshlrev_b32_e32 v142, 16, v185
	v_and_b32_e32 v143, 0xffff0000, v185
	v_lshlrev_b32_e32 v146, 16, v186
	v_and_b32_e32 v147, 0xffff0000, v186
	v_lshlrev_b32_e32 v138, 16, v187
	v_and_b32_e32 v139, 0xffff0000, v187
	v_lshlrev_b32_e32 v140, 16, v188
	v_and_b32_e32 v141, 0xffff0000, v188
	v_lshlrev_b32_e32 v130, 16, v189
	v_and_b32_e32 v131, 0xffff0000, v189
	v_lshlrev_b32_e32 v132, 16, v190
	v_and_b32_e32 v133, 0xffff0000, v190
	v_lshlrev_b32_e32 v120, 16, v191
	v_and_b32_e32 v121, 0xffff0000, v191
	v_lshlrev_b32_e32 v122, 16, v192
	v_and_b32_e32 v123, 0xffff0000, v192
	v_lshlrev_b32_e32 v114, 16, v193
	v_and_b32_e32 v115, 0xffff0000, v193
	v_lshlrev_b32_e32 v116, 16, v194
	v_and_b32_e32 v117, 0xffff0000, v194
	v_lshlrev_b32_e32 v108, 16, v195
	v_and_b32_e32 v109, 0xffff0000, v195
	v_lshlrev_b32_e32 v110, 16, v196
	v_and_b32_e32 v111, 0xffff0000, v196
	v_lshlrev_b32_e32 v100, 16, v197
	v_and_b32_e32 v101, 0xffff0000, v197
	v_lshlrev_b32_e32 v102, 16, v198
	v_and_b32_e32 v103, 0xffff0000, v198
	v_lshlrev_b32_e32 v96, 16, v199
	v_and_b32_e32 v97, 0xffff0000, v199
	v_mov_b32_e32 v0, s18
	ds_read_b128 v[64:67], v0
	ds_read_b128 v[72:75], v0 offset:16
	ds_read_b128 v[80:83], v0 offset:32
	ds_read_b128 v[164:167], v0 offset:48
	s_waitcnt lgkmcnt(3)
	v_mov_b32_e32 v0, v67
	v_pk_mul_f32 v[152:153], v[28:29], v[0:1] op_sel_hi:[1,0]
	s_waitcnt lgkmcnt(2)
	v_mov_b32_e32 v0, v75
	v_pk_mul_f32 v[136:137], v[28:29], v[0:1] op_sel_hi:[1,0]
	s_waitcnt lgkmcnt(1)
	v_mov_b32_e32 v0, v83
	v_pk_mul_f32 v[168:169], v[28:29], v[64:65] op_sel_hi:[1,0]
	v_pk_mul_f32 v[118:119], v[28:29], v[0:1] op_sel_hi:[1,0]
	s_waitcnt lgkmcnt(0)
	v_mov_b32_e32 v0, v167
	v_pk_mul_f32 v[98:99], v[28:29], v[0:1] op_sel_hi:[1,0]
	v_pk_fma_f32 v[90:91], v[168:169], v[154:155], v[90:91]
	v_cvt_f32_ubyte0_e32 v0, vcc_lo
	v_pk_add_f32 v[90:91], v[90:91], v[124:125] neg_lo:[0,1] neg_hi:[0,1]
	v_div_scale_f32 v124, vcc, v0, v0, 1.0
	v_rcp_f32_e32 v125, v124
	v_pk_mul_f32 v[32:33], v[168:169], v[154:155]
	v_pk_mul_f32 v[158:159], v[28:29], v[64:65] op_sel:[0,1]
	v_pk_mul_f32 v[156:157], v[28:29], v[66:67] op_sel_hi:[1,0]
	v_fma_f32 v154, -v124, v125, 1.0
	v_fmac_f32_e32 v125, v154, v125
	v_div_scale_f32 v154, vcc, 1.0, v0, 1.0
	v_mul_f32_e32 v155, v154, v125
	v_fma_f32 v163, -v124, v155, v154
	v_fmac_f32_e32 v155, v163, v125
	v_fma_f32 v124, -v124, v155, v154
	v_div_fmas_f32 v124, v124, v125, v155
	v_div_fixup_f32 v0, v124, v0, 1.0
	v_pk_fma_f32 v[124:125], v[0:1], v[90:91], v[32:33] op_sel_hi:[0,1,1] neg_lo:[0,0,1] neg_hi:[0,0,1]
	s_mov_b32 vcc_lo, 0x17701000
	v_cvt_pk_bf16_f32 v0, v124, v125
	v_add_co_u32_e32 v124, vcc, vcc_lo, v94
	v_pk_fma_f32 v[90:91], v[158:159], v[142:143], v[90:91]
	s_nop 0
	v_addc_co_u32_e32 v125, vcc, 0, v95, vcc
	global_store_dword v[124:125], v0, off offset:-4096
	v_cvt_f32_ubyte0_e32 v0, s28
	v_pk_add_f32 v[60:61], v[90:91], v[60:61] neg_lo:[0,1] neg_hi:[0,1]
	v_div_scale_f32 v90, vcc, v0, v0, 1.0
	v_rcp_f32_e32 v91, v90
	v_pk_mul_f32 v[62:63], v[158:159], v[142:143]
	s_min_u32 s28, s29, 15
	s_add_i32 s28, s28, 1
	v_fma_f32 v142, -v90, v91, 1.0
	v_fmac_f32_e32 v91, v142, v91
	v_div_scale_f32 v142, vcc, 1.0, v0, 1.0
	v_mul_f32_e32 v143, v142, v91
	v_fma_f32 v154, -v90, v143, v142
	v_fmac_f32_e32 v143, v154, v91
	v_fma_f32 v90, -v90, v143, v142
	v_div_fmas_f32 v90, v90, v91, v143
	v_div_fixup_f32 v0, v90, v0, 1.0
	v_pk_fma_f32 v[90:91], v[0:1], v[60:61], v[62:63] op_sel_hi:[0,1,1] neg_lo:[0,0,1] neg_hi:[0,0,1]
	v_cvt_pk_bf16_f32 v0, v90, v91
	global_store_dword v[124:125], v0, off
	v_pk_fma_f32 v[60:61], v[156:157], v[146:147], v[60:61]
	v_cvt_f32_ubyte0_e32 v0, s28
	v_pk_add_f32 v[58:59], v[60:61], v[58:59] neg_lo:[0,1] neg_hi:[0,1]
	v_div_scale_f32 v60, s[28:29], v0, v0, 1.0
	v_rcp_f32_e32 v61, v60
	v_pk_mul_f32 v[64:65], v[156:157], v[146:147]
	s_mov_b32 s28, 0x17703000
	v_pk_mul_f32 v[66:67], v[152:153], v[138:139]
	v_fma_f32 v90, -v60, v61, 1.0
	v_fmac_f32_e32 v61, v90, v61
	v_div_scale_f32 v90, vcc, 1.0, v0, 1.0
	v_mul_f32_e32 v91, v90, v61
	v_fma_f32 v124, -v60, v91, v90
	v_fmac_f32_e32 v91, v124, v61
	v_fma_f32 v60, -v60, v91, v90
	v_div_fmas_f32 v60, v60, v61, v91
	v_div_fixup_f32 v0, v60, v0, 1.0
	v_pk_fma_f32 v[60:61], v[0:1], v[58:59], v[64:65] op_sel_hi:[0,1,1] neg_lo:[0,0,1] neg_hi:[0,0,1]
	v_cvt_pk_bf16_f32 v0, v60, v61
	v_add_co_u32_e32 v60, vcc, s28, v94
	s_min_u32 s28, s76, 15
	s_nop 0
	v_addc_co_u32_e32 v61, vcc, 0, v95, vcc
	s_add_i32 s28, s28, 1
	global_store_dword v[60:61], v0, off offset:-4096
	v_pk_fma_f32 v[58:59], v[152:153], v[138:139], v[58:59]
	v_cvt_f32_ubyte0_e32 v0, s28
	v_pk_add_f32 v[56:57], v[58:59], v[56:57] neg_lo:[0,1] neg_hi:[0,1]
	v_div_scale_f32 v58, s[28:29], v0, v0, 1.0
	v_rcp_f32_e32 v59, v58
	s_min_u32 s28, s77, 15
	v_pk_mul_f32 v[150:151], v[28:29], v[72:73] op_sel_hi:[1,0]
	s_add_i32 s28, s28, 1
	v_fma_f32 v90, -v58, v59, 1.0
	v_fmac_f32_e32 v59, v90, v59
	v_div_scale_f32 v90, vcc, 1.0, v0, 1.0
	v_mul_f32_e32 v91, v90, v59
	v_fma_f32 v124, -v58, v91, v90
	v_fmac_f32_e32 v91, v124, v59
	v_fma_f32 v58, -v58, v91, v90
	v_div_fmas_f32 v58, v58, v59, v91
	v_div_fixup_f32 v0, v58, v0, 1.0
	v_pk_fma_f32 v[58:59], v[0:1], v[56:57], v[66:67] op_sel_hi:[0,1,1] neg_lo:[0,0,1] neg_hi:[0,0,1]
	v_cvt_pk_bf16_f32 v0, v58, v59
	global_store_dword v[60:61], v0, off
	v_pk_fma_f32 v[56:57], v[150:151], v[140:141], v[56:57]
	v_cvt_f32_ubyte0_e32 v0, s28
	v_pk_add_f32 v[54:55], v[56:57], v[54:55] neg_lo:[0,1] neg_hi:[0,1]
	v_div_scale_f32 v56, s[28:29], v0, v0, 1.0
	v_rcp_f32_e32 v57, v56
	v_pk_mul_f32 v[68:69], v[150:151], v[140:141]
	s_mov_b32 s28, 0x17705000
	v_pk_mul_f32 v[148:149], v[28:29], v[72:73] op_sel:[0,1]
	v_fma_f32 v58, -v56, v57, 1.0
	v_fmac_f32_e32 v57, v58, v57
	v_div_scale_f32 v58, vcc, 1.0, v0, 1.0
	v_mul_f32_e32 v59, v58, v57
	v_fma_f32 v60, -v56, v59, v58
	v_fmac_f32_e32 v59, v60, v57
	v_fma_f32 v56, -v56, v59, v58
	v_div_fmas_f32 v56, v56, v57, v59
	v_div_fixup_f32 v0, v56, v0, 1.0
	v_pk_fma_f32 v[56:57], v[0:1], v[54:55], v[68:69] op_sel_hi:[0,1,1] neg_lo:[0,0,1] neg_hi:[0,0,1]
	v_cvt_pk_bf16_f32 v0, v56, v57
	v_add_co_u32_e32 v56, vcc, s28, v94
	v_pk_fma_f32 v[54:55], v[148:149], v[130:131], v[54:55]
	s_nop 0
	v_addc_co_u32_e32 v57, vcc, 0, v95, vcc
	global_store_dword v[56:57], v0, off offset:-4096
	v_cvt_f32_ubyte0_e32 v0, s26
	v_pk_add_f32 v[50:51], v[54:55], v[50:51] neg_lo:[0,1] neg_hi:[0,1]
	v_div_scale_f32 v54, s[28:29], v0, v0, 1.0
	v_rcp_f32_e32 v55, v54
	v_pk_mul_f32 v[70:71], v[148:149], v[130:131]
	s_min_u32 s26, s27, 15
	v_pk_mul_f32 v[144:145], v[28:29], v[74:75] op_sel_hi:[1,0]
	v_fma_f32 v58, -v54, v55, 1.0
	v_fmac_f32_e32 v55, v58, v55
	v_div_scale_f32 v58, vcc, 1.0, v0, 1.0
	v_mul_f32_e32 v59, v58, v55
	v_fma_f32 v60, -v54, v59, v58
	v_fmac_f32_e32 v59, v60, v55
	v_fma_f32 v54, -v54, v59, v58
	v_div_fmas_f32 v54, v54, v55, v59
	v_div_fixup_f32 v0, v54, v0, 1.0
	v_pk_fma_f32 v[54:55], v[0:1], v[50:51], v[70:71] op_sel_hi:[0,1,1] neg_lo:[0,0,1] neg_hi:[0,0,1]
	v_cvt_pk_bf16_f32 v0, v54, v55
	s_add_i32 s26, s26, 1
	global_store_dword v[56:57], v0, off
	v_pk_fma_f32 v[50:51], v[144:145], v[132:133], v[50:51]
	v_cvt_f32_ubyte0_e32 v0, s26
	v_pk_add_f32 v[50:51], v[50:51], v[52:53] neg_lo:[0,1] neg_hi:[0,1]
	v_div_scale_f32 v52, s[26:27], v0, v0, 1.0
	v_rcp_f32_e32 v53, v52
	v_pk_mul_f32 v[72:73], v[144:145], v[132:133]
	s_mov_b32 s26, 0x17707000
	v_pk_mul_f32 v[74:75], v[136:137], v[120:121]
	v_fma_f32 v54, -v52, v53, 1.0
	v_fmac_f32_e32 v53, v54, v53
	v_div_scale_f32 v54, vcc, 1.0, v0, 1.0
	v_mul_f32_e32 v55, v54, v53
	v_fma_f32 v56, -v52, v55, v54
	v_fmac_f32_e32 v55, v56, v53
	v_fma_f32 v52, -v52, v55, v54
	v_div_fmas_f32 v52, v52, v53, v55
	v_div_fixup_f32 v0, v52, v0, 1.0
	v_pk_fma_f32 v[52:53], v[0:1], v[50:51], v[72:73] op_sel_hi:[0,1,1] neg_lo:[0,0,1] neg_hi:[0,0,1]
	v_cvt_pk_bf16_f32 v0, v52, v53
	v_add_co_u32_e32 v52, vcc, s26, v94
	s_min_u32 s26, s82, 15
	s_nop 0
	v_addc_co_u32_e32 v53, vcc, 0, v95, vcc
	s_add_i32 s26, s26, 1
	global_store_dword v[52:53], v0, off offset:-4096
	v_pk_fma_f32 v[50:51], v[136:137], v[120:121], v[50:51]
	v_cvt_f32_ubyte0_e32 v0, s26
	v_pk_add_f32 v[48:49], v[50:51], v[48:49] neg_lo:[0,1] neg_hi:[0,1]
	v_div_scale_f32 v50, s[26:27], v0, v0, 1.0
	v_rcp_f32_e32 v51, v50
	s_min_u32 s26, s87, 15
	v_pk_mul_f32 v[134:135], v[28:29], v[80:81] op_sel_hi:[1,0]
	s_add_i32 s26, s26, 1
	v_fma_f32 v54, -v50, v51, 1.0
	v_fmac_f32_e32 v51, v54, v51
	v_div_scale_f32 v54, vcc, 1.0, v0, 1.0
	v_mul_f32_e32 v55, v54, v51
	v_fma_f32 v56, -v50, v55, v54
	v_fmac_f32_e32 v55, v56, v51
	v_fma_f32 v50, -v50, v55, v54
	v_div_fmas_f32 v50, v50, v51, v55
	v_div_fixup_f32 v0, v50, v0, 1.0
	v_pk_fma_f32 v[50:51], v[0:1], v[48:49], v[74:75] op_sel_hi:[0,1,1] neg_lo:[0,0,1] neg_hi:[0,0,1]
	v_cvt_pk_bf16_f32 v0, v50, v51
	global_store_dword v[52:53], v0, off
	v_pk_fma_f32 v[48:49], v[134:135], v[122:123], v[48:49]
	v_cvt_f32_ubyte0_e32 v0, s26
	v_pk_add_f32 v[46:47], v[48:49], v[46:47] neg_lo:[0,1] neg_hi:[0,1]
	v_div_scale_f32 v48, s[26:27], v0, v0, 1.0
	v_rcp_f32_e32 v49, v48
	v_pk_mul_f32 v[76:77], v[134:135], v[122:123]
	s_mov_b32 s26, 0x17709000
	v_pk_mul_f32 v[128:129], v[28:29], v[80:81] op_sel:[0,1]
	v_fma_f32 v50, -v48, v49, 1.0
	v_fmac_f32_e32 v49, v50, v49
	v_div_scale_f32 v50, vcc, 1.0, v0, 1.0
	v_mul_f32_e32 v51, v50, v49
	v_fma_f32 v52, -v48, v51, v50
	v_fmac_f32_e32 v51, v52, v49
	v_fma_f32 v48, -v48, v51, v50
	v_div_fmas_f32 v48, v48, v49, v51
	v_div_fixup_f32 v0, v48, v0, 1.0
	v_pk_fma_f32 v[48:49], v[0:1], v[46:47], v[76:77] op_sel_hi:[0,1,1] neg_lo:[0,0,1] neg_hi:[0,0,1]
	v_cvt_pk_bf16_f32 v0, v48, v49
	v_add_co_u32_e32 v48, vcc, s26, v94
	s_min_u32 s26, s72, 15
	s_nop 0
	v_addc_co_u32_e32 v49, vcc, 0, v95, vcc
	s_add_i32 s26, s26, 1
	global_store_dword v[48:49], v0, off offset:-4096
	v_pk_fma_f32 v[46:47], v[128:129], v[114:115], v[46:47]
	v_cvt_f32_ubyte0_e32 v0, s26
	v_pk_add_f32 v[44:45], v[46:47], v[44:45] neg_lo:[0,1] neg_hi:[0,1]
	v_div_scale_f32 v46, s[26:27], v0, v0, 1.0
	v_rcp_f32_e32 v47, v46
	v_pk_mul_f32 v[78:79], v[128:129], v[114:115]
	s_min_u32 s26, s81, 15
	v_pk_mul_f32 v[126:127], v[28:29], v[82:83] op_sel_hi:[1,0]
	v_fma_f32 v50, -v46, v47, 1.0
	v_fmac_f32_e32 v47, v50, v47
	v_div_scale_f32 v50, vcc, 1.0, v0, 1.0
	v_mul_f32_e32 v51, v50, v47
	v_fma_f32 v52, -v46, v51, v50
	v_fmac_f32_e32 v51, v52, v47
	v_fma_f32 v46, -v46, v51, v50
	v_div_fmas_f32 v46, v46, v47, v51
	v_div_fixup_f32 v0, v46, v0, 1.0
	v_pk_fma_f32 v[46:47], v[0:1], v[44:45], v[78:79] op_sel_hi:[0,1,1] neg_lo:[0,0,1] neg_hi:[0,0,1]
	v_cvt_pk_bf16_f32 v0, v46, v47
	s_add_i32 s26, s26, 1
	global_store_dword v[48:49], v0, off
	v_pk_fma_f32 v[44:45], v[126:127], v[116:117], v[44:45]
	v_cvt_f32_ubyte0_e32 v0, s26
	v_pk_add_f32 v[42:43], v[44:45], v[42:43] neg_lo:[0,1] neg_hi:[0,1]
	v_div_scale_f32 v44, s[26:27], v0, v0, 1.0
	v_rcp_f32_e32 v45, v44
	v_pk_mul_f32 v[80:81], v[126:127], v[116:117]
	s_mov_b32 s26, 0x1770b000
	v_pk_mul_f32 v[82:83], v[118:119], v[108:109]
	v_fma_f32 v46, -v44, v45, 1.0
	v_fmac_f32_e32 v45, v46, v45
	v_div_scale_f32 v46, vcc, 1.0, v0, 1.0
	v_mul_f32_e32 v47, v46, v45
	v_fma_f32 v48, -v44, v47, v46
	v_fmac_f32_e32 v47, v48, v45
	v_fma_f32 v44, -v44, v47, v46
	v_div_fmas_f32 v44, v44, v45, v47
	v_div_fixup_f32 v0, v44, v0, 1.0
	v_pk_fma_f32 v[44:45], v[0:1], v[42:43], v[80:81] op_sel_hi:[0,1,1] neg_lo:[0,0,1] neg_hi:[0,0,1]
	v_cvt_pk_bf16_f32 v0, v44, v45
	v_add_co_u32_e32 v44, vcc, s26, v94
	s_min_u32 s26, s70, 15
	s_nop 0
	v_addc_co_u32_e32 v45, vcc, 0, v95, vcc
	s_add_i32 s26, s26, 1
	global_store_dword v[44:45], v0, off offset:-4096
	v_pk_fma_f32 v[42:43], v[118:119], v[108:109], v[42:43]
	v_cvt_f32_ubyte0_e32 v0, s26
	v_pk_add_f32 v[40:41], v[42:43], v[40:41] neg_lo:[0,1] neg_hi:[0,1]
	v_div_scale_f32 v42, s[26:27], v0, v0, 1.0
	v_rcp_f32_e32 v43, v42
	s_min_u32 s26, s71, 15
	v_pk_mul_f32 v[112:113], v[28:29], v[164:165] op_sel_hi:[1,0]
	s_add_i32 s26, s26, 1
	v_fma_f32 v46, -v42, v43, 1.0
	v_fmac_f32_e32 v43, v46, v43
	v_div_scale_f32 v46, vcc, 1.0, v0, 1.0
	v_mul_f32_e32 v47, v46, v43
	v_fma_f32 v48, -v42, v47, v46
	v_fmac_f32_e32 v47, v48, v43
	v_fma_f32 v42, -v42, v47, v46
	v_div_fmas_f32 v42, v42, v43, v47
	v_div_fixup_f32 v0, v42, v0, 1.0
	v_pk_fma_f32 v[42:43], v[0:1], v[40:41], v[82:83] op_sel_hi:[0,1,1] neg_lo:[0,0,1] neg_hi:[0,0,1]
	v_cvt_pk_bf16_f32 v0, v42, v43
	global_store_dword v[44:45], v0, off
	v_pk_fma_f32 v[40:41], v[112:113], v[110:111], v[40:41]
	v_cvt_f32_ubyte0_e32 v0, s26
	v_pk_add_f32 v[38:39], v[40:41], v[38:39] neg_lo:[0,1] neg_hi:[0,1]
	v_div_scale_f32 v40, s[26:27], v0, v0, 1.0
	v_rcp_f32_e32 v41, v40
	v_pk_mul_f32 v[84:85], v[112:113], v[110:111]
	s_mov_b32 s26, 0x1770d000
	v_pk_mul_f32 v[106:107], v[28:29], v[164:165] op_sel:[0,1]
	v_fma_f32 v42, -v40, v41, 1.0
	v_fmac_f32_e32 v41, v42, v41
	v_div_scale_f32 v42, vcc, 1.0, v0, 1.0
	v_mul_f32_e32 v43, v42, v41
	v_fma_f32 v44, -v40, v43, v42
	v_fmac_f32_e32 v43, v44, v41
	v_fma_f32 v40, -v40, v43, v42
	v_div_fmas_f32 v40, v40, v41, v43
	v_div_fixup_f32 v0, v40, v0, 1.0
	v_pk_fma_f32 v[40:41], v[0:1], v[38:39], v[84:85] op_sel_hi:[0,1,1] neg_lo:[0,0,1] neg_hi:[0,0,1]
	v_cvt_pk_bf16_f32 v0, v40, v41
	v_add_co_u32_e32 v40, vcc, s26, v94
	v_pk_fma_f32 v[38:39], v[106:107], v[100:101], v[38:39]
	s_nop 0
	v_addc_co_u32_e32 v41, vcc, 0, v95, vcc
	global_store_dword v[40:41], v0, off offset:-4096
	v_cvt_f32_ubyte0_e32 v0, s0
	v_pk_add_f32 v[36:37], v[38:39], v[36:37] neg_lo:[0,1] neg_hi:[0,1]
	v_div_scale_f32 v38, s[26:27], v0, v0, 1.0
	v_rcp_f32_e32 v39, v38
	v_pk_mul_f32 v[86:87], v[106:107], v[100:101]
	s_min_u32 s0, s1, 15
	v_pk_mul_f32 v[104:105], v[28:29], v[166:167] op_sel_hi:[1,0]
	v_fma_f32 v42, -v38, v39, 1.0
	v_fmac_f32_e32 v39, v42, v39
	v_div_scale_f32 v42, vcc, 1.0, v0, 1.0
	v_mul_f32_e32 v43, v42, v39
	v_fma_f32 v44, -v38, v43, v42
	v_fmac_f32_e32 v43, v44, v39
	v_fma_f32 v38, -v38, v43, v42
	v_div_fmas_f32 v38, v38, v39, v43
	v_div_fixup_f32 v0, v38, v0, 1.0
	v_pk_fma_f32 v[38:39], v[0:1], v[36:37], v[86:87] op_sel_hi:[0,1,1] neg_lo:[0,0,1] neg_hi:[0,0,1]
	v_cvt_pk_bf16_f32 v0, v38, v39
	s_add_i32 s0, s0, 1
	global_store_dword v[40:41], v0, off
	v_pk_fma_f32 v[36:37], v[104:105], v[102:103], v[36:37]
	v_cvt_f32_ubyte0_e32 v0, s0
	v_pk_add_f32 v[34:35], v[36:37], v[34:35] neg_lo:[0,1] neg_hi:[0,1]
	v_div_scale_f32 v36, s[0:1], v0, v0, 1.0
	v_rcp_f32_e32 v37, v36
	v_pk_mul_f32 v[88:89], v[104:105], v[102:103]
	s_mov_b32 s0, 0x1770f000
	v_pk_mul_f32 v[92:93], v[98:99], v[96:97]
	v_fma_f32 v38, -v36, v37, 1.0
	v_fmac_f32_e32 v37, v38, v37
	v_div_scale_f32 v38, vcc, 1.0, v0, 1.0
	v_mul_f32_e32 v39, v38, v37
	v_fma_f32 v40, -v36, v39, v38
	v_fmac_f32_e32 v39, v40, v37
	v_fma_f32 v36, -v36, v39, v38
	v_div_fmas_f32 v36, v36, v37, v39
	v_div_fixup_f32 v0, v36, v0, 1.0
	v_pk_fma_f32 v[36:37], v[0:1], v[34:35], v[88:89] op_sel_hi:[0,1,1] neg_lo:[0,0,1] neg_hi:[0,0,1]
	v_pk_fma_f32 v[34:35], v[98:99], v[96:97], v[34:35]
	v_cvt_pk_bf16_f32 v0, v36, v37
	v_add_co_u32_e32 v36, vcc, s0, v94
	v_pk_add_f32 v[90:91], v[34:35], v[4:5] neg_lo:[0,1] neg_hi:[0,1]
	s_mov_b32 s0, 0x3d800000
	s_add_u32 s16, s16, 0x10000
	v_addc_co_u32_e32 v37, vcc, 0, v95, vcc
	v_pk_fma_f32 v[4:5], v[90:91], s[0:1], v[92:93] op_sel_hi:[1,0,1] neg_lo:[0,0,1] neg_hi:[0,0,1]
	s_addc_u32 s17, s17, 0
	s_add_i32 s19, s19, 16
	s_add_i32 s18, s18, 64
	global_store_dword v[36:37], v0, off offset:-4096
	v_cvt_pk_bf16_f32 v0, v4, v5
	global_store_dword v[36:37], v0, off
	s_cmp_eq_u32 s16, 0x40000
	v_mov_b64_e32 v[4:5], v[92:93]
	v_mov_b64_e32 v[34:35], v[88:89]
	v_mov_b64_e32 v[36:37], v[86:87]
	v_mov_b64_e32 v[38:39], v[84:85]
	v_mov_b64_e32 v[40:41], v[82:83]
	v_mov_b64_e32 v[42:43], v[80:81]
	v_mov_b64_e32 v[44:45], v[78:79]
	v_mov_b64_e32 v[46:47], v[76:77]
	v_mov_b64_e32 v[48:49], v[74:75]
	v_mov_b64_e32 v[52:53], v[72:73]
	v_mov_b64_e32 v[50:51], v[70:71]
	v_mov_b64_e32 v[54:55], v[68:69]
	v_mov_b64_e32 v[56:57], v[66:67]
	v_mov_b64_e32 v[58:59], v[64:65]
	v_mov_b64_e32 v[60:61], v[62:63]
	v_mov_b64_e32 v[124:125], v[32:33]
	s_cbranch_scc0 .LBB0_382
